# NSA window sweep interior tiles rewritten in place like the selected sweep (no accumulator copies, QK of both halves up front)
# speedup vs baseline: 1.1403x; 1.0053x over previous
.Lnsw_keep0:
	v_mov_b32_e32 v167, v173
	v_cndmask_b32_e64 v174, v173, v206, s[38:39]
	v_sub_f32_e32 v80, v80, v174
	v_exp_f32_e32 v80, v80
	v_sub_f32_e32 v81, v81, v174
	v_exp_f32_e32 v81, v81
	v_add_f32_e32 v213, 0, v80
	v_sub_f32_e32 v82, v82, v174
	v_exp_f32_e32 v82, v82
	v_add_f32_e32 v213, v81, v213
	v_sub_f32_e32 v83, v83, v174
	v_exp_f32_e32 v83, v83
	v_add_f32_e32 v213, v82, v213
	v_cvt_pk_bf16_f32 v176, v80, v81
	v_sub_f32_e32 v84, v84, v174
	v_exp_f32_e32 v84, v84
	v_add_f32_e32 v213, v83, v213
	v_sub_f32_e32 v85, v85, v174
	v_exp_f32_e32 v85, v85
	v_add_f32_e32 v213, v84, v213
	v_cvt_pk_bf16_f32 v177, v82, v83
	v_sub_f32_e32 v86, v86, v174
	v_exp_f32_e32 v86, v86
	v_add_f32_e32 v213, v85, v213
	v_sub_f32_e32 v87, v87, v174
	v_exp_f32_e32 v87, v87
	v_add_f32_e32 v213, v86, v213
	v_cvt_pk_bf16_f32 v178, v84, v85
	v_sub_f32_e32 v88, v88, v174
	v_exp_f32_e32 v88, v88
	v_add_f32_e32 v213, v87, v213
	v_sub_f32_e32 v89, v89, v174
	v_exp_f32_e32 v89, v89
	v_add_f32_e32 v213, v88, v213
	v_cvt_pk_bf16_f32 v179, v86, v87
	v_sub_f32_e32 v90, v90, v174
	v_exp_f32_e32 v90, v90
	v_add_f32_e32 v213, v89, v213
	v_mfma_f32_32x32x16_bf16 v[32:47], v[64:67], v[176:179], v[32:47]
	v_mfma_f32_32x32x16_bf16 v[16:31], v[68:71], v[176:179], v[16:31]
	v_sub_f32_e32 v91, v91, v174
	v_exp_f32_e32 v91, v91
	v_add_f32_e32 v213, v90, v213
	v_cvt_pk_bf16_f32 v180, v88, v89
	v_sub_f32_e32 v92, v92, v174
	v_exp_f32_e32 v92, v92
	v_add_f32_e32 v213, v91, v213
	v_sub_f32_e32 v93, v93, v174
	v_exp_f32_e32 v93, v93
	v_add_f32_e32 v213, v92, v213
	v_cvt_pk_bf16_f32 v181, v90, v91
	v_sub_f32_e32 v94, v94, v174
	v_exp_f32_e32 v94, v94
	v_add_f32_e32 v213, v93, v213
	v_sub_f32_e32 v95, v95, v174
	v_exp_f32_e32 v95, v95
	v_add_f32_e32 v213, v94, v213
	v_cvt_pk_bf16_f32 v182, v92, v93
	v_add_f32_e32 v213, v95, v213
	v_cvt_pk_bf16_f32 v183, v94, v95
	v_fmac_f32_e32 v213, v169, v0
	v_mov_b32_e32 v169, v213
	s_nop 0
	v_mfma_f32_32x32x16_bf16 v[32:47], v[72:75], v[180:183], v[32:47]
	v_mfma_f32_32x32x16_bf16 v[16:31], v[76:79], v[180:183], v[16:31]
	v_max3_f32 v0, v48, v49, v50
	v_max3_f32 v2, v56, v57, v58
	v_max3_f32 v0, v0, v51, v52
	v_max3_f32 v2, v2, v59, v60
	v_max3_f32 v0, v0, v53, v54
	v_max3_f32 v2, v2, v61, v62
	v_max3_f32 v0, v0, v55, v63
	v_max_f32_e32 v0, v0, v2
	v_cndmask_b32_e64 v0, v0, v202, s[38:39]
	ds_bpermute_b32 v2, v119, v0
	s_waitcnt lgkmcnt(0)
	v_max3_f32 v173, v167, v0, v2
	v_sub_f32_e32 v0, v167, v173
	v_exp_f32_e32 v0, v0
	v_cmp_eq_f32_e32 vcc, v173, v167
	s_cmp_eq_u64 vcc, exec
	s_cbranch_scc1 .Lnsw_keep1
	v_pk_mul_f32 v[46:47], v[46:47], v[0:1] op_sel_hi:[1,0]
	v_pk_mul_f32 v[44:45], v[44:45], v[0:1] op_sel_hi:[1,0]
	v_pk_mul_f32 v[42:43], v[42:43], v[0:1] op_sel_hi:[1,0]
	v_pk_mul_f32 v[40:41], v[40:41], v[0:1] op_sel_hi:[1,0]
	v_pk_mul_f32 v[38:39], v[38:39], v[0:1] op_sel_hi:[1,0]
	v_pk_mul_f32 v[36:37], v[36:37], v[0:1] op_sel_hi:[1,0]
	v_pk_mul_f32 v[34:35], v[34:35], v[0:1] op_sel_hi:[1,0]
	v_pk_mul_f32 v[32:33], v[32:33], v[0:1] op_sel_hi:[1,0]
	v_pk_mul_f32 v[30:31], v[30:31], v[0:1] op_sel_hi:[1,0]
	v_pk_mul_f32 v[28:29], v[28:29], v[0:1] op_sel_hi:[1,0]
	v_pk_mul_f32 v[26:27], v[26:27], v[0:1] op_sel_hi:[1,0]
	v_pk_mul_f32 v[24:25], v[24:25], v[0:1] op_sel_hi:[1,0]
	v_pk_mul_f32 v[22:23], v[22:23], v[0:1] op_sel_hi:[1,0]
	v_pk_mul_f32 v[20:21], v[20:21], v[0:1] op_sel_hi:[1,0]
	v_pk_mul_f32 v[18:19], v[18:19], v[0:1] op_sel_hi:[1,0]
	v_pk_mul_f32 v[16:17], v[16:17], v[0:1] op_sel_hi:[1,0]
.Lnsw_keep1:
	v_mov_b32_e32 v167, v173
	v_cndmask_b32_e64 v174, v173, v206, s[38:39]
	v_sub_f32_e32 v48, v48, v174
	v_exp_f32_e32 v48, v48
	v_sub_f32_e32 v49, v49, v174
	v_exp_f32_e32 v49, v49
	v_add_f32_e32 v213, 0, v48
	v_sub_f32_e32 v50, v50, v174
	v_exp_f32_e32 v50, v50
	v_add_f32_e32 v213, v49, v213
	v_sub_f32_e32 v51, v51, v174
	v_exp_f32_e32 v51, v51
	v_add_f32_e32 v213, v50, v213
	v_cvt_pk_bf16_f32 v80, v48, v49
	v_sub_f32_e32 v52, v52, v174
	v_exp_f32_e32 v52, v52
	v_add_f32_e32 v213, v51, v213
	v_sub_f32_e32 v53, v53, v174
	v_exp_f32_e32 v53, v53
	v_add_f32_e32 v213, v52, v213
	v_cvt_pk_bf16_f32 v81, v50, v51
	v_sub_f32_e32 v54, v54, v174
	v_exp_f32_e32 v54, v54
	v_add_f32_e32 v213, v53, v213
	v_sub_f32_e32 v55, v55, v174
	v_exp_f32_e32 v55, v55
	v_add_f32_e32 v213, v54, v213
	v_cvt_pk_bf16_f32 v82, v52, v53
	v_sub_f32_e32 v56, v56, v174
	v_exp_f32_e32 v56, v56
	v_add_f32_e32 v213, v55, v213
	v_sub_f32_e32 v57, v57, v174
	v_exp_f32_e32 v57, v57
	v_add_f32_e32 v213, v56, v213
	v_cvt_pk_bf16_f32 v83, v54, v55
	v_sub_f32_e32 v58, v58, v174
	v_exp_f32_e32 v58, v58
	v_add_f32_e32 v213, v57, v213
	v_mfma_f32_32x32x16_bf16 v[32:47], v[220:223], v[80:83], v[32:47]
	v_mfma_f32_32x32x16_bf16 v[16:31], v[224:227], v[80:83], v[16:31]
	v_sub_f32_e32 v59, v59, v174
	v_exp_f32_e32 v59, v59
	v_add_f32_e32 v213, v58, v213
	v_cvt_pk_bf16_f32 v84, v56, v57
	v_sub_f32_e32 v60, v60, v174
	v_exp_f32_e32 v60, v60
	v_add_f32_e32 v213, v59, v213
	v_sub_f32_e32 v61, v61, v174
	v_exp_f32_e32 v61, v61
	v_add_f32_e32 v213, v60, v213
	v_cvt_pk_bf16_f32 v85, v58, v59
	v_sub_f32_e32 v62, v62, v174
	v_exp_f32_e32 v62, v62
	v_add_f32_e32 v213, v61, v213
	v_sub_f32_e32 v63, v63, v174
	v_exp_f32_e32 v63, v63
	v_add_f32_e32 v213, v62, v213
	v_cvt_pk_bf16_f32 v86, v60, v61
	v_add_f32_e32 v213, v63, v213
	v_cvt_pk_bf16_f32 v87, v62, v63
	v_fmac_f32_e32 v213, v169, v0
	v_mov_b32_e32 v169, v213
	s_nop 0
	v_mfma_f32_32x32x16_bf16 v[32:47], v[228:231], v[84:87], v[32:47]
	v_mfma_f32_32x32x16_bf16 v[16:31], v[232:235], v[84:87], v[16:31]
	s_branch .LBB0_296

.LBB0_307:
	s_and_b64 vcc, exec, s[4:5]
	s_cbranch_vccz .Lnsw1_edgeback
	v_mad_u32_u24 v0, v117, s37, v14
	v_lshl_add_u32 v215, v159, 1, v15
	ds_read_b128 v[220:223], v0
	ds_read_b128 v[236:239], v0 offset:4608
	ds_read_b128 v[224:227], v0 offset:32
	ds_read_b128 v[240:243], v0 offset:4640
	ds_read_b128 v[228:231], v0 offset:64
	ds_read_b128 v[244:247], v0 offset:4672
	ds_read_b128 v[232:235], v0 offset:96
	ds_read_b128 v[248:251], v0 offset:4704
	v_add_u32_e32 v214, 0x3000, v215
	v_add_u32_e32 v215, 0x2000, v215
	ds_read2_b64 v[64:67], v215 offset0:128 offset1:130
	ds_read2_b64 v[68:71], v214 offset0:192 offset1:194
	ds_read2_b64 v[72:75], v215 offset0:132 offset1:134
	ds_read2_b64 v[76:79], v214 offset0:196 offset1:198
	s_waitcnt lgkmcnt(11)
	v_mfma_f32_32x32x16_bf16 v[80:95], v[220:223], v[96:99], 0
	s_waitcnt lgkmcnt(10)
	v_mfma_f32_32x32x16_bf16 v[48:63], v[236:239], v[96:99], 0
	s_waitcnt lgkmcnt(9)
	v_mfma_f32_32x32x16_bf16 v[80:95], v[224:227], v[100:103], v[80:95]
	s_waitcnt lgkmcnt(8)
	v_mfma_f32_32x32x16_bf16 v[48:63], v[240:243], v[100:103], v[48:63]
	s_waitcnt lgkmcnt(7)
	v_mfma_f32_32x32x16_bf16 v[80:95], v[228:231], v[104:107], v[80:95]
	s_waitcnt lgkmcnt(6)
	v_mfma_f32_32x32x16_bf16 v[48:63], v[244:247], v[104:107], v[48:63]
	s_waitcnt lgkmcnt(5)
	v_mfma_f32_32x32x16_bf16 v[80:95], v[232:235], v[108:111], v[80:95]
	s_waitcnt lgkmcnt(4)
	v_mfma_f32_32x32x16_bf16 v[48:63], v[248:251], v[108:111], v[48:63]
	ds_read2_b64 v[220:223], v215 offset0:136 offset1:138
	ds_read2_b64 v[224:227], v214 offset0:200 offset1:202
	ds_read2_b64 v[228:231], v215 offset0:140 offset1:142
	ds_read2_b64 v[232:235], v214 offset0:204 offset1:206
	s_nop 7
	v_max3_f32 v0, v80, v81, v82
	v_max3_f32 v216, v88, v89, v90
	v_max3_f32 v0, v0, v83, v84
	v_max3_f32 v216, v216, v91, v92
	v_max3_f32 v0, v0, v85, v86
	v_max3_f32 v216, v216, v93, v94
	v_max3_f32 v0, v0, v87, v95
	v_max_f32_e32 v0, v0, v216
	ds_bpermute_b32 v216, v119, v0
	s_waitcnt lgkmcnt(0)
	v_max3_f32 v173, v168, v0, v216
	v_sub_f32_e32 v0, v168, v173
	v_exp_f32_e32 v0, v0
	v_cmp_eq_f32_e32 vcc, v173, v168
	s_cmp_eq_u64 vcc, exec
	s_cbranch_scc1 .Lnsw1_keep0
	v_pk_mul_f32 v[46:47], v[46:47], v[0:1] op_sel_hi:[1,0]
	v_pk_mul_f32 v[44:45], v[44:45], v[0:1] op_sel_hi:[1,0]
	v_pk_mul_f32 v[42:43], v[42:43], v[0:1] op_sel_hi:[1,0]
	v_pk_mul_f32 v[40:41], v[40:41], v[0:1] op_sel_hi:[1,0]
	v_pk_mul_f32 v[38:39], v[38:39], v[0:1] op_sel_hi:[1,0]
	v_pk_mul_f32 v[36:37], v[36:37], v[0:1] op_sel_hi:[1,0]
	v_pk_mul_f32 v[34:35], v[34:35], v[0:1] op_sel_hi:[1,0]
	v_pk_mul_f32 v[32:33], v[32:33], v[0:1] op_sel_hi:[1,0]
	v_pk_mul_f32 v[30:31], v[30:31], v[0:1] op_sel_hi:[1,0]
	v_pk_mul_f32 v[28:29], v[28:29], v[0:1] op_sel_hi:[1,0]
	v_pk_mul_f32 v[26:27], v[26:27], v[0:1] op_sel_hi:[1,0]
	v_pk_mul_f32 v[24:25], v[24:25], v[0:1] op_sel_hi:[1,0]
	v_pk_mul_f32 v[22:23], v[22:23], v[0:1] op_sel_hi:[1,0]
	v_pk_mul_f32 v[20:21], v[20:21], v[0:1] op_sel_hi:[1,0]
	v_pk_mul_f32 v[18:19], v[18:19], v[0:1] op_sel_hi:[1,0]
	v_pk_mul_f32 v[16:17], v[16:17], v[0:1] op_sel_hi:[1,0]
.Lnsw1_keep0:
	v_mov_b32_e32 v168, v173
	v_mov_b32_e32 v174, v173
	v_sub_f32_e32 v80, v80, v174
	v_exp_f32_e32 v80, v80
	v_sub_f32_e32 v81, v81, v174
	v_exp_f32_e32 v81, v81
	v_add_f32_e32 v213, 0, v80
	v_sub_f32_e32 v82, v82, v174
	v_exp_f32_e32 v82, v82
	v_add_f32_e32 v213, v81, v213
	v_sub_f32_e32 v83, v83, v174
	v_exp_f32_e32 v83, v83
	v_add_f32_e32 v213, v82, v213
	v_cvt_pk_bf16_f32 v176, v80, v81
	v_sub_f32_e32 v84, v84, v174
	v_exp_f32_e32 v84, v84
	v_add_f32_e32 v213, v83, v213
	v_sub_f32_e32 v85, v85, v174
	v_exp_f32_e32 v85, v85
	v_add_f32_e32 v213, v84, v213
	v_cvt_pk_bf16_f32 v177, v82, v83
	v_sub_f32_e32 v86, v86, v174
	v_exp_f32_e32 v86, v86
	v_add_f32_e32 v213, v85, v213
	v_sub_f32_e32 v87, v87, v174
	v_exp_f32_e32 v87, v87
	v_add_f32_e32 v213, v86, v213
	v_cvt_pk_bf16_f32 v178, v84, v85
	v_sub_f32_e32 v88, v88, v174
	v_exp_f32_e32 v88, v88
	v_add_f32_e32 v213, v87, v213
	v_sub_f32_e32 v89, v89, v174
	v_exp_f32_e32 v89, v89
	v_add_f32_e32 v213, v88, v213
	v_cvt_pk_bf16_f32 v179, v86, v87
	v_sub_f32_e32 v90, v90, v174
	v_exp_f32_e32 v90, v90
	v_add_f32_e32 v213, v89, v213
	v_mfma_f32_32x32x16_bf16 v[32:47], v[64:67], v[176:179], v[32:47]
	v_mfma_f32_32x32x16_bf16 v[16:31], v[68:71], v[176:179], v[16:31]
	v_sub_f32_e32 v91, v91, v174
	v_exp_f32_e32 v91, v91
	v_add_f32_e32 v213, v90, v213
	v_cvt_pk_bf16_f32 v180, v88, v89
	v_sub_f32_e32 v92, v92, v174
	v_exp_f32_e32 v92, v92
	v_add_f32_e32 v213, v91, v213
	v_sub_f32_e32 v93, v93, v174
	v_exp_f32_e32 v93, v93
	v_add_f32_e32 v213, v92, v213
	v_cvt_pk_bf16_f32 v181, v90, v91
	v_sub_f32_e32 v94, v94, v174
	v_exp_f32_e32 v94, v94
	v_add_f32_e32 v213, v93, v213
	v_sub_f32_e32 v95, v95, v174
	v_exp_f32_e32 v95, v95
	v_add_f32_e32 v213, v94, v213
	v_cvt_pk_bf16_f32 v182, v92, v93
	v_add_f32_e32 v213, v95, v213
	v_cvt_pk_bf16_f32 v183, v94, v95
	v_fmac_f32_e32 v213, v169, v0
	v_mov_b32_e32 v169, v213
	s_nop 0
	v_mfma_f32_32x32x16_bf16 v[32:47], v[72:75], v[180:183], v[32:47]
	v_mfma_f32_32x32x16_bf16 v[16:31], v[76:79], v[180:183], v[16:31]
	v_max3_f32 v0, v48, v49, v50
	v_max3_f32 v216, v56, v57, v58
	v_max3_f32 v0, v0, v51, v52
	v_max3_f32 v216, v216, v59, v60
	v_max3_f32 v0, v0, v53, v54
	v_max3_f32 v216, v216, v61, v62
	v_max3_f32 v0, v0, v55, v63
	v_max_f32_e32 v0, v0, v216
	ds_bpermute_b32 v216, v119, v0
	s_waitcnt lgkmcnt(0)
	v_max3_f32 v173, v168, v0, v216
	v_sub_f32_e32 v0, v168, v173
	v_exp_f32_e32 v0, v0
	v_cmp_eq_f32_e32 vcc, v173, v168
	s_cmp_eq_u64 vcc, exec
	s_cbranch_scc1 .Lnsw1_keep1
	v_pk_mul_f32 v[46:47], v[46:47], v[0:1] op_sel_hi:[1,0]
	v_pk_mul_f32 v[44:45], v[44:45], v[0:1] op_sel_hi:[1,0]
	v_pk_mul_f32 v[42:43], v[42:43], v[0:1] op_sel_hi:[1,0]
	v_pk_mul_f32 v[40:41], v[40:41], v[0:1] op_sel_hi:[1,0]
	v_pk_mul_f32 v[38:39], v[38:39], v[0:1] op_sel_hi:[1,0]
	v_pk_mul_f32 v[36:37], v[36:37], v[0:1] op_sel_hi:[1,0]
	v_pk_mul_f32 v[34:35], v[34:35], v[0:1] op_sel_hi:[1,0]
	v_pk_mul_f32 v[32:33], v[32:33], v[0:1] op_sel_hi:[1,0]
	v_pk_mul_f32 v[30:31], v[30:31], v[0:1] op_sel_hi:[1,0]
	v_pk_mul_f32 v[28:29], v[28:29], v[0:1] op_sel_hi:[1,0]
	v_pk_mul_f32 v[26:27], v[26:27], v[0:1] op_sel_hi:[1,0]
	v_pk_mul_f32 v[24:25], v[24:25], v[0:1] op_sel_hi:[1,0]
	v_pk_mul_f32 v[22:23], v[22:23], v[0:1] op_sel_hi:[1,0]
	v_pk_mul_f32 v[20:21], v[20:21], v[0:1] op_sel_hi:[1,0]
	v_pk_mul_f32 v[18:19], v[18:19], v[0:1] op_sel_hi:[1,0]
	v_pk_mul_f32 v[16:17], v[16:17], v[0:1] op_sel_hi:[1,0]
.Lnsw1_keep1:
	v_mov_b32_e32 v168, v173
	v_mov_b32_e32 v174, v173
	v_sub_f32_e32 v48, v48, v174
	v_exp_f32_e32 v48, v48
	v_sub_f32_e32 v49, v49, v174
	v_exp_f32_e32 v49, v49
	v_add_f32_e32 v213, 0, v48
	v_sub_f32_e32 v50, v50, v174
	v_exp_f32_e32 v50, v50
	v_add_f32_e32 v213, v49, v213
	v_sub_f32_e32 v51, v51, v174
	v_exp_f32_e32 v51, v51
	v_add_f32_e32 v213, v50, v213
	v_cvt_pk_bf16_f32 v80, v48, v49
	v_sub_f32_e32 v52, v52, v174
	v_exp_f32_e32 v52, v52
	v_add_f32_e32 v213, v51, v213
	v_sub_f32_e32 v53, v53, v174
	v_exp_f32_e32 v53, v53
	v_add_f32_e32 v213, v52, v213
	v_cvt_pk_bf16_f32 v81, v50, v51
	v_sub_f32_e32 v54, v54, v174
	v_exp_f32_e32 v54, v54
	v_add_f32_e32 v213, v53, v213
	v_sub_f32_e32 v55, v55, v174
	v_exp_f32_e32 v55, v55
	v_add_f32_e32 v213, v54, v213
	v_cvt_pk_bf16_f32 v82, v52, v53
	v_sub_f32_e32 v56, v56, v174
	v_exp_f32_e32 v56, v56
	v_add_f32_e32 v213, v55, v213
	v_sub_f32_e32 v57, v57, v174
	v_exp_f32_e32 v57, v57
	v_add_f32_e32 v213, v56, v213
	v_cvt_pk_bf16_f32 v83, v54, v55
	v_sub_f32_e32 v58, v58, v174
	v_exp_f32_e32 v58, v58
	v_add_f32_e32 v213, v57, v213
	v_mfma_f32_32x32x16_bf16 v[32:47], v[220:223], v[80:83], v[32:47]
	v_mfma_f32_32x32x16_bf16 v[16:31], v[224:227], v[80:83], v[16:31]
	v_sub_f32_e32 v59, v59, v174
	v_exp_f32_e32 v59, v59
	v_add_f32_e32 v213, v58, v213
	v_cvt_pk_bf16_f32 v84, v56, v57
	v_sub_f32_e32 v60, v60, v174
	v_exp_f32_e32 v60, v60
	v_add_f32_e32 v213, v59, v213
	v_sub_f32_e32 v61, v61, v174
	v_exp_f32_e32 v61, v61
	v_add_f32_e32 v213, v60, v213
	v_cvt_pk_bf16_f32 v85, v58, v59
	v_sub_f32_e32 v62, v62, v174
	v_exp_f32_e32 v62, v62
	v_add_f32_e32 v213, v61, v213
	v_sub_f32_e32 v63, v63, v174
	v_exp_f32_e32 v63, v63
	v_add_f32_e32 v213, v62, v213
	v_cvt_pk_bf16_f32 v86, v60, v61
	v_add_f32_e32 v213, v63, v213
	v_cvt_pk_bf16_f32 v87, v62, v63
	v_fmac_f32_e32 v213, v169, v0
	v_mov_b32_e32 v169, v213
	s_nop 0
	v_mfma_f32_32x32x16_bf16 v[32:47], v[228:231], v[84:87], v[32:47]
	v_mfma_f32_32x32x16_bf16 v[16:31], v[232:235], v[84:87], v[16:31]
	s_branch .LBB0_314
.Lnsw1_edgeback:
	s_nop 15
	v_mov_b64_e32 v[16:17], v[64:65]
	v_mov_b64_e32 v[32:33], v[48:49]
	v_mov_b64_e32 v[18:19], v[66:67]
	v_mov_b64_e32 v[20:21], v[68:69]
	v_mov_b64_e32 v[22:23], v[70:71]
	v_mov_b64_e32 v[24:25], v[72:73]
	v_mov_b64_e32 v[26:27], v[74:75]
	v_mov_b64_e32 v[28:29], v[76:77]
	v_mov_b64_e32 v[30:31], v[78:79]
	v_mov_b64_e32 v[34:35], v[50:51]
	v_mov_b64_e32 v[36:37], v[52:53]
	v_mov_b64_e32 v[38:39], v[54:55]
	v_mov_b64_e32 v[40:41], v[56:57]
	v_mov_b64_e32 v[42:43], v[58:59]
	v_mov_b64_e32 v[44:45], v[60:61]
	v_mov_b64_e32 v[46:47], v[62:63]
	v_mov_b32_e32 v169, v81
	v_mov_b32_e32 v168, v170
.LBB0_314:
	s_xor_b32 s4, s14, 1
	s_mulk_i32 s4, 0x4800
	v_lshl_add_u32 v0, v158, 1, s4
	s_waitcnt vmcnt(3)
	ds_write_b128 v0, v[6:9]
	v_lshl_add_u32 v6, v160, 1, s4
	s_cmp_lt_i32 s12, s10
	s_waitcnt vmcnt(2)
	ds_write_b128 v6, v[2:5]
	s_waitcnt vmcnt(1)
	ds_write_b128 v0, v[10:13] offset:9216
	s_waitcnt vmcnt(0)
	ds_write_b128 v6, v[112:115] offset:9216
	s_waitcnt lgkmcnt(0)
	s_barrier
	s_cbranch_scc0 .Lnsw1_exit
	s_mov_b32 s12, s13
	s_branch .LBB0_301
.Lnsw1_exit:
	s_nop 7
	s_nop 7
	v_mov_b64_e32 v[64:65], v[16:17]
	v_mov_b64_e32 v[48:49], v[32:33]
	v_mov_b64_e32 v[66:67], v[18:19]
	v_mov_b64_e32 v[68:69], v[20:21]
	v_mov_b64_e32 v[70:71], v[22:23]
	v_mov_b64_e32 v[72:73], v[24:25]
	v_mov_b64_e32 v[74:75], v[26:27]
	v_mov_b64_e32 v[76:77], v[28:29]
	v_mov_b64_e32 v[78:79], v[30:31]
	v_mov_b64_e32 v[50:51], v[34:35]
	v_mov_b64_e32 v[52:53], v[36:37]
	v_mov_b64_e32 v[54:55], v[38:39]
	v_mov_b64_e32 v[56:57], v[40:41]
	v_mov_b64_e32 v[58:59], v[42:43]
	v_mov_b64_e32 v[60:61], v[44:45]
	v_mov_b64_e32 v[62:63], v[46:47]
	v_mov_b32_e32 v81, v169
	v_mov_b32_e32 v170, v168
	s_branch .LBB0_317
